# v63 + FF1 epilogue: the eight per-row-group rstd LDS reads issued together at the top of the epilogue (one wait) instead of one LDS round trip per row-group
# baseline (speedup 1.0000x reference)
.LBB0_215:
	v_mov_b32_e32 v0, v144
	v_mov_b32_e32 v142, v145
	s_lshl_b32 s50, s50, 8
	s_or_b32 s50, s50, s62
	s_ashr_i32 s55, s54, 31
	v_add_u32_e32 v148, s61, v0
	v_lshl_add_u32 v142, v142, 3, s50
	s_lshl_b64 s[50:51], s[54:55], 21
	v_readlane_b32 s54, v236, 59
	s_add_u32 s54, s54, s50
	v_readlane_b32 s50, v236, 56
	v_and_b32_e32 v149, 0xff, v148
	s_addc_u32 s55, s50, s51
	v_lshlrev_b32_e32 v0, 13, v149
	s_add_i32 s50, 0, 0x20400
	v_lshl_add_u64 v[150:151], s[54:55], 0, v[0:1]
	v_lshl_add_u32 v238, v149, 2, s50
	ds_read_b32 v0, v238
	ds_read_b32 v239, v238 offset:64
	ds_read_b32 v240, v238 offset:128
	ds_read_b32 v241, v238 offset:192
	ds_read_b32 v242, v238 offset:512
	ds_read_b32 v243, v238 offset:576
	ds_read_b32 v244, v238 offset:640
	ds_read_b32 v245, v238 offset:704
	v_ashrrev_i32_e32 v143, 31, v142
	v_lshlrev_b64 v[142:143], 1, v[142:143]
	v_lshl_add_u64 v[150:151], v[150:151], 0, v[142:143]
	s_movk_i32 s51, 0x80
	s_waitcnt lgkmcnt(0)
	v_pk_mul_f32 v[124:125], v[124:125], v[0:1] op_sel_hi:[1,0]
	v_pk_mul_f32 v[122:123], v[122:123], v[0:1] op_sel_hi:[1,0]
	v_pk_mul_f32 v[128:129], v[128:129], v[0:1] op_sel_hi:[1,0]
	v_pk_mul_f32 v[126:127], v[126:127], v[0:1] op_sel_hi:[1,0]
	v_max_f32_e32 v122, 0, v122
	v_max_f32_e32 v126, 0, v126
	v_max_f32_e32 v123, 0, v123
	v_max_f32_e32 v127, 0, v127
	v_max_f32_e32 v124, 0, v124
	v_max_f32_e32 v128, 0, v128
	v_max_f32_e32 v125, 0, v125
	v_max_f32_e32 v129, 0, v129
	v_pk_mul_f32 v[122:123], v[122:123], v[122:123]
	v_pk_mul_f32 v[126:127], v[126:127], v[126:127]
	v_pk_mul_f32 v[124:125], v[124:125], v[124:125]
	v_pk_mul_f32 v[128:129], v[128:129], v[128:129]
	v_pk_mul_f32 v[114:115], v[114:115], v[0:1] op_sel_hi:[1,0]
	v_cvt_pk_bf16_f32 v122, v122, v123
	v_cvt_pk_bf16_f32 v123, v124, v125
	v_cvt_pk_bf16_f32 v124, v126, v127
	v_cvt_pk_bf16_f32 v125, v128, v129
	v_pk_mul_f32 v[120:121], v[120:121], v[0:1] op_sel_hi:[1,0]
	v_pk_mul_f32 v[118:119], v[118:119], v[0:1] op_sel_hi:[1,0]
	v_pk_mul_f32 v[116:117], v[116:117], v[0:1] op_sel_hi:[1,0]
	v_max_f32_e32 v114, 0, v114
	v_max_f32_e32 v115, 0, v115
	global_store_dwordx4 v[150:151], v[122:125], off
	v_max_f32_e32 v118, 0, v118
	v_max_f32_e32 v119, 0, v119
	v_pk_mul_f32 v[122:123], v[114:115], v[114:115]
	v_max_f32_e32 v114, 0, v120
	v_max_f32_e32 v116, 0, v116
	v_max_f32_e32 v115, 0, v121
	v_max_f32_e32 v117, 0, v117
	v_pk_mul_f32 v[118:119], v[118:119], v[118:119]
	v_pk_mul_f32 v[120:121], v[114:115], v[114:115]
	v_pk_mul_f32 v[124:125], v[116:117], v[116:117]
	v_cvt_pk_bf16_f32 v114, v118, v119
	v_cvt_pk_bf16_f32 v115, v120, v121
	v_cvt_pk_bf16_f32 v116, v122, v123
	v_cvt_pk_bf16_f32 v117, v124, v125
	v_add_u32_e32 v0, 16, v148
	global_store_dwordx4 v[150:151], v[114:117], off offset:256
	s_andn2_b64 vcc, exec, s[48:49]
	s_nop 0
	v_and_b32_e32 v116, 0xff, v0
	v_lshlrev_b32_e32 v0, 13, v116
	v_lshl_add_u64 v[114:115], s[54:55], 0, v[0:1]
	v_mov_b32_e32 v0, v239
	s_nop 0
	v_lshl_add_u64 v[114:115], v[114:115], 0, v[142:143]
	s_waitcnt lgkmcnt(0)
	v_pk_mul_f32 v[106:107], v[106:107], v[0:1] op_sel_hi:[1,0]
	v_pk_mul_f32 v[112:113], v[112:113], v[0:1] op_sel_hi:[1,0]
	v_pk_mul_f32 v[110:111], v[110:111], v[0:1] op_sel_hi:[1,0]
	v_pk_mul_f32 v[108:109], v[108:109], v[0:1] op_sel_hi:[1,0]
	v_max_f32_e32 v106, 0, v106
	v_max_f32_e32 v107, 0, v107
	v_max_f32_e32 v110, 0, v110
	v_max_f32_e32 v111, 0, v111
	v_pk_mul_f32 v[116:117], v[106:107], v[106:107]
	v_max_f32_e32 v106, 0, v112
	v_max_f32_e32 v108, 0, v108
	v_max_f32_e32 v107, 0, v113
	v_max_f32_e32 v109, 0, v109
	v_pk_mul_f32 v[110:111], v[110:111], v[110:111]
	v_pk_mul_f32 v[112:113], v[106:107], v[106:107]
	v_pk_mul_f32 v[118:119], v[108:109], v[108:109]
	v_pk_mul_f32 v[98:99], v[98:99], v[0:1] op_sel_hi:[1,0]
	v_cvt_pk_bf16_f32 v106, v110, v111
	v_cvt_pk_bf16_f32 v107, v112, v113
	v_cvt_pk_bf16_f32 v108, v116, v117
	v_cvt_pk_bf16_f32 v109, v118, v119
	v_pk_mul_f32 v[104:105], v[104:105], v[0:1] op_sel_hi:[1,0]
	v_pk_mul_f32 v[102:103], v[102:103], v[0:1] op_sel_hi:[1,0]
	v_pk_mul_f32 v[100:101], v[100:101], v[0:1] op_sel_hi:[1,0]
	v_max_f32_e32 v98, 0, v98
	v_max_f32_e32 v99, 0, v99
	global_store_dwordx4 v[114:115], v[106:109], off
	v_max_f32_e32 v102, 0, v102
	v_max_f32_e32 v103, 0, v103
	v_pk_mul_f32 v[106:107], v[98:99], v[98:99]
	v_max_f32_e32 v98, 0, v104
	v_max_f32_e32 v100, 0, v100
	v_max_f32_e32 v99, 0, v105
	v_max_f32_e32 v101, 0, v101
	v_pk_mul_f32 v[102:103], v[102:103], v[102:103]
	v_pk_mul_f32 v[104:105], v[98:99], v[98:99]
	v_pk_mul_f32 v[108:109], v[100:101], v[100:101]
	v_cvt_pk_bf16_f32 v98, v102, v103
	v_cvt_pk_bf16_f32 v99, v104, v105
	v_cvt_pk_bf16_f32 v100, v106, v107
	v_cvt_pk_bf16_f32 v101, v108, v109
	v_add_u32_e32 v0, 32, v148
	global_store_dwordx4 v[114:115], v[98:101], off offset:256
	s_nop 1
	v_and_b32_e32 v100, 0xff, v0
	v_lshlrev_b32_e32 v0, 13, v100
	v_lshl_add_u64 v[98:99], s[54:55], 0, v[0:1]
	v_mov_b32_e32 v0, v240
	s_nop 0
	v_lshl_add_u64 v[98:99], v[98:99], 0, v[142:143]
	s_waitcnt lgkmcnt(0)
	v_pk_mul_f32 v[90:91], v[90:91], v[0:1] op_sel_hi:[1,0]
	v_pk_mul_f32 v[96:97], v[96:97], v[0:1] op_sel_hi:[1,0]
	v_pk_mul_f32 v[94:95], v[94:95], v[0:1] op_sel_hi:[1,0]
	v_pk_mul_f32 v[92:93], v[92:93], v[0:1] op_sel_hi:[1,0]
	v_max_f32_e32 v90, 0, v90
	v_max_f32_e32 v91, 0, v91
	v_max_f32_e32 v94, 0, v94
	v_max_f32_e32 v95, 0, v95
	v_pk_mul_f32 v[100:101], v[90:91], v[90:91]
	v_max_f32_e32 v90, 0, v96
	v_max_f32_e32 v92, 0, v92
	v_max_f32_e32 v91, 0, v97
	v_max_f32_e32 v93, 0, v93
	v_pk_mul_f32 v[94:95], v[94:95], v[94:95]
	v_pk_mul_f32 v[96:97], v[90:91], v[90:91]
	v_pk_mul_f32 v[102:103], v[92:93], v[92:93]
	v_pk_mul_f32 v[82:83], v[82:83], v[0:1] op_sel_hi:[1,0]
	v_cvt_pk_bf16_f32 v90, v94, v95
	v_cvt_pk_bf16_f32 v91, v96, v97
	v_cvt_pk_bf16_f32 v92, v100, v101
	v_cvt_pk_bf16_f32 v93, v102, v103
	v_pk_mul_f32 v[88:89], v[88:89], v[0:1] op_sel_hi:[1,0]
	v_pk_mul_f32 v[86:87], v[86:87], v[0:1] op_sel_hi:[1,0]
	v_pk_mul_f32 v[84:85], v[84:85], v[0:1] op_sel_hi:[1,0]
	v_max_f32_e32 v82, 0, v82
	v_max_f32_e32 v83, 0, v83
	global_store_dwordx4 v[98:99], v[90:93], off
	v_max_f32_e32 v86, 0, v86
	v_max_f32_e32 v87, 0, v87
	v_pk_mul_f32 v[90:91], v[82:83], v[82:83]
	v_max_f32_e32 v82, 0, v88
	v_max_f32_e32 v84, 0, v84
	v_max_f32_e32 v83, 0, v89
	v_max_f32_e32 v85, 0, v85
	v_pk_mul_f32 v[86:87], v[86:87], v[86:87]
	v_pk_mul_f32 v[88:89], v[82:83], v[82:83]
	v_pk_mul_f32 v[92:93], v[84:85], v[84:85]
	v_cvt_pk_bf16_f32 v82, v86, v87
	v_cvt_pk_bf16_f32 v83, v88, v89
	v_cvt_pk_bf16_f32 v84, v90, v91
	v_cvt_pk_bf16_f32 v85, v92, v93
	v_add_u32_e32 v0, 48, v148
	global_store_dwordx4 v[98:99], v[82:85], off offset:256
	s_nop 1
	v_and_b32_e32 v84, 0xff, v0
	v_lshlrev_b32_e32 v0, 13, v84
	v_lshl_add_u64 v[82:83], s[54:55], 0, v[0:1]
	v_mov_b32_e32 v0, v241
	s_nop 0
	v_lshl_add_u64 v[82:83], v[82:83], 0, v[142:143]
	s_waitcnt lgkmcnt(0)
	v_pk_mul_f32 v[74:75], v[74:75], v[0:1] op_sel_hi:[1,0]
	v_pk_mul_f32 v[80:81], v[80:81], v[0:1] op_sel_hi:[1,0]
	v_pk_mul_f32 v[78:79], v[78:79], v[0:1] op_sel_hi:[1,0]
	v_pk_mul_f32 v[76:77], v[76:77], v[0:1] op_sel_hi:[1,0]
	v_max_f32_e32 v74, 0, v74
	v_max_f32_e32 v75, 0, v75
	v_max_f32_e32 v78, 0, v78
	v_max_f32_e32 v79, 0, v79
	v_pk_mul_f32 v[84:85], v[74:75], v[74:75]
	v_max_f32_e32 v74, 0, v80
	v_max_f32_e32 v76, 0, v76
	v_max_f32_e32 v75, 0, v81
	v_max_f32_e32 v77, 0, v77
	v_pk_mul_f32 v[78:79], v[78:79], v[78:79]
	v_pk_mul_f32 v[80:81], v[74:75], v[74:75]
	v_pk_mul_f32 v[86:87], v[76:77], v[76:77]
	v_pk_mul_f32 v[66:67], v[66:67], v[0:1] op_sel_hi:[1,0]
	v_cvt_pk_bf16_f32 v74, v78, v79
	v_cvt_pk_bf16_f32 v75, v80, v81
	v_cvt_pk_bf16_f32 v76, v84, v85
	v_cvt_pk_bf16_f32 v77, v86, v87
	v_pk_mul_f32 v[72:73], v[72:73], v[0:1] op_sel_hi:[1,0]
	v_pk_mul_f32 v[70:71], v[70:71], v[0:1] op_sel_hi:[1,0]
	v_pk_mul_f32 v[68:69], v[68:69], v[0:1] op_sel_hi:[1,0]
	v_max_f32_e32 v66, 0, v66
	v_max_f32_e32 v67, 0, v67
	global_store_dwordx4 v[82:83], v[74:77], off
	v_max_f32_e32 v70, 0, v70
	v_max_f32_e32 v71, 0, v71
	v_pk_mul_f32 v[74:75], v[66:67], v[66:67]
	v_max_f32_e32 v66, 0, v72
	v_max_f32_e32 v68, 0, v68
	v_max_f32_e32 v67, 0, v73
	v_max_f32_e32 v69, 0, v69
	v_pk_mul_f32 v[70:71], v[70:71], v[70:71]
	v_pk_mul_f32 v[72:73], v[66:67], v[66:67]
	v_pk_mul_f32 v[76:77], v[68:69], v[68:69]
	v_cvt_pk_bf16_f32 v66, v70, v71
	v_cvt_pk_bf16_f32 v67, v72, v73
	v_cvt_pk_bf16_f32 v68, v74, v75
	v_cvt_pk_bf16_f32 v69, v76, v77
	global_store_dwordx4 v[82:83], v[66:69], off offset:256
	s_nop 1
	v_bitop3_b32 v68, v148, s51, v195 bitop3:0x6c
	v_lshlrev_b32_e32 v0, 13, v68
	v_lshl_add_u64 v[66:67], s[54:55], 0, v[0:1]
	v_mov_b32_e32 v0, v242
	s_nop 0
	v_lshl_add_u64 v[66:67], v[66:67], 0, v[142:143]
	s_waitcnt lgkmcnt(0)
	v_pk_mul_f32 v[58:59], v[58:59], v[0:1] op_sel_hi:[1,0]
	v_pk_mul_f32 v[64:65], v[64:65], v[0:1] op_sel_hi:[1,0]
	v_pk_mul_f32 v[62:63], v[62:63], v[0:1] op_sel_hi:[1,0]
	v_pk_mul_f32 v[60:61], v[60:61], v[0:1] op_sel_hi:[1,0]
	v_max_f32_e32 v58, 0, v58
	v_max_f32_e32 v59, 0, v59
	v_max_f32_e32 v62, 0, v62
	v_max_f32_e32 v63, 0, v63
	v_pk_mul_f32 v[68:69], v[58:59], v[58:59]
	v_max_f32_e32 v58, 0, v64
	v_max_f32_e32 v60, 0, v60
	v_max_f32_e32 v59, 0, v65
	v_max_f32_e32 v61, 0, v61
	v_pk_mul_f32 v[62:63], v[62:63], v[62:63]
	v_pk_mul_f32 v[64:65], v[58:59], v[58:59]
	v_pk_mul_f32 v[70:71], v[60:61], v[60:61]
	v_pk_mul_f32 v[50:51], v[50:51], v[0:1] op_sel_hi:[1,0]
	v_cvt_pk_bf16_f32 v58, v62, v63
	v_cvt_pk_bf16_f32 v59, v64, v65
	v_cvt_pk_bf16_f32 v60, v68, v69
	v_cvt_pk_bf16_f32 v61, v70, v71
	v_pk_mul_f32 v[56:57], v[56:57], v[0:1] op_sel_hi:[1,0]
	v_pk_mul_f32 v[54:55], v[54:55], v[0:1] op_sel_hi:[1,0]
	v_pk_mul_f32 v[52:53], v[52:53], v[0:1] op_sel_hi:[1,0]
	v_max_f32_e32 v50, 0, v50
	v_max_f32_e32 v51, 0, v51
	global_store_dwordx4 v[66:67], v[58:61], off
	v_max_f32_e32 v54, 0, v54
	v_max_f32_e32 v55, 0, v55
	v_pk_mul_f32 v[58:59], v[50:51], v[50:51]
	v_max_f32_e32 v50, 0, v56
	v_max_f32_e32 v52, 0, v52
	v_max_f32_e32 v51, 0, v57
	v_max_f32_e32 v53, 0, v53
	v_pk_mul_f32 v[54:55], v[54:55], v[54:55]
	v_pk_mul_f32 v[56:57], v[50:51], v[50:51]
	v_pk_mul_f32 v[60:61], v[52:53], v[52:53]
	v_cvt_pk_bf16_f32 v50, v54, v55
	v_cvt_pk_bf16_f32 v51, v56, v57
	v_cvt_pk_bf16_f32 v52, v58, v59
	v_cvt_pk_bf16_f32 v53, v60, v61
	v_add_u32_e32 v0, 0x90, v148
	global_store_dwordx4 v[66:67], v[50:53], off offset:256
	s_nop 1
	v_and_b32_e32 v52, 0xff, v0
	v_lshlrev_b32_e32 v0, 13, v52
	v_lshl_add_u64 v[50:51], s[54:55], 0, v[0:1]
	v_mov_b32_e32 v0, v243
	s_nop 0
	v_lshl_add_u64 v[50:51], v[50:51], 0, v[142:143]
	s_waitcnt lgkmcnt(0)
	v_pk_mul_f32 v[42:43], v[42:43], v[0:1] op_sel_hi:[1,0]
	v_pk_mul_f32 v[48:49], v[48:49], v[0:1] op_sel_hi:[1,0]
	v_pk_mul_f32 v[46:47], v[46:47], v[0:1] op_sel_hi:[1,0]
	v_pk_mul_f32 v[44:45], v[44:45], v[0:1] op_sel_hi:[1,0]
	v_max_f32_e32 v42, 0, v42
	v_max_f32_e32 v43, 0, v43
	v_max_f32_e32 v46, 0, v46
	v_max_f32_e32 v47, 0, v47
	v_pk_mul_f32 v[52:53], v[42:43], v[42:43]
	v_max_f32_e32 v42, 0, v48
	v_max_f32_e32 v44, 0, v44
	v_max_f32_e32 v43, 0, v49
	v_max_f32_e32 v45, 0, v45
	v_pk_mul_f32 v[46:47], v[46:47], v[46:47]
	v_pk_mul_f32 v[48:49], v[42:43], v[42:43]
	v_pk_mul_f32 v[54:55], v[44:45], v[44:45]
	v_pk_mul_f32 v[34:35], v[34:35], v[0:1] op_sel_hi:[1,0]
	v_cvt_pk_bf16_f32 v42, v46, v47
	v_cvt_pk_bf16_f32 v43, v48, v49
	v_cvt_pk_bf16_f32 v44, v52, v53
	v_cvt_pk_bf16_f32 v45, v54, v55
	v_pk_mul_f32 v[40:41], v[40:41], v[0:1] op_sel_hi:[1,0]
	v_pk_mul_f32 v[38:39], v[38:39], v[0:1] op_sel_hi:[1,0]
	v_pk_mul_f32 v[36:37], v[36:37], v[0:1] op_sel_hi:[1,0]
	v_max_f32_e32 v34, 0, v34
	v_max_f32_e32 v35, 0, v35
	global_store_dwordx4 v[50:51], v[42:45], off
	v_max_f32_e32 v38, 0, v38
	v_max_f32_e32 v39, 0, v39
	v_pk_mul_f32 v[42:43], v[34:35], v[34:35]
	v_max_f32_e32 v34, 0, v40
	v_max_f32_e32 v36, 0, v36
	v_max_f32_e32 v35, 0, v41
	v_max_f32_e32 v37, 0, v37
	v_pk_mul_f32 v[38:39], v[38:39], v[38:39]
	v_pk_mul_f32 v[40:41], v[34:35], v[34:35]
	v_pk_mul_f32 v[44:45], v[36:37], v[36:37]
	v_cvt_pk_bf16_f32 v34, v38, v39
	v_cvt_pk_bf16_f32 v35, v40, v41
	v_cvt_pk_bf16_f32 v36, v42, v43
	v_cvt_pk_bf16_f32 v37, v44, v45
	v_add_u32_e32 v0, 0xa0, v148
	global_store_dwordx4 v[50:51], v[34:37], off offset:256
	s_nop 1
	v_and_b32_e32 v36, 0xff, v0
	v_lshlrev_b32_e32 v0, 13, v36
	v_lshl_add_u64 v[34:35], s[54:55], 0, v[0:1]
	v_mov_b32_e32 v0, v244
	s_nop 0
	v_lshl_add_u64 v[34:35], v[34:35], 0, v[142:143]
	s_waitcnt lgkmcnt(0)
	v_pk_mul_f32 v[26:27], v[26:27], v[0:1] op_sel_hi:[1,0]
	v_pk_mul_f32 v[32:33], v[32:33], v[0:1] op_sel_hi:[1,0]
	v_pk_mul_f32 v[30:31], v[30:31], v[0:1] op_sel_hi:[1,0]
	v_pk_mul_f32 v[28:29], v[28:29], v[0:1] op_sel_hi:[1,0]
	v_max_f32_e32 v26, 0, v26
	v_max_f32_e32 v27, 0, v27
	v_max_f32_e32 v30, 0, v30
	v_max_f32_e32 v31, 0, v31
	v_pk_mul_f32 v[36:37], v[26:27], v[26:27]
	v_max_f32_e32 v26, 0, v32
	v_max_f32_e32 v28, 0, v28
	v_max_f32_e32 v27, 0, v33
	v_max_f32_e32 v29, 0, v29
	v_pk_mul_f32 v[30:31], v[30:31], v[30:31]
	v_pk_mul_f32 v[32:33], v[26:27], v[26:27]
	v_pk_mul_f32 v[38:39], v[28:29], v[28:29]
	v_pk_mul_f32 v[18:19], v[18:19], v[0:1] op_sel_hi:[1,0]
	v_cvt_pk_bf16_f32 v26, v30, v31
	v_cvt_pk_bf16_f32 v27, v32, v33
	v_cvt_pk_bf16_f32 v28, v36, v37
	v_cvt_pk_bf16_f32 v29, v38, v39
	v_pk_mul_f32 v[24:25], v[24:25], v[0:1] op_sel_hi:[1,0]
	v_pk_mul_f32 v[22:23], v[22:23], v[0:1] op_sel_hi:[1,0]
	v_pk_mul_f32 v[20:21], v[20:21], v[0:1] op_sel_hi:[1,0]
	v_max_f32_e32 v18, 0, v18
	v_max_f32_e32 v19, 0, v19
	global_store_dwordx4 v[34:35], v[26:29], off
	v_max_f32_e32 v22, 0, v22
	v_max_f32_e32 v23, 0, v23
	v_pk_mul_f32 v[26:27], v[18:19], v[18:19]
	v_max_f32_e32 v18, 0, v24
	v_max_f32_e32 v20, 0, v20
	v_max_f32_e32 v19, 0, v25
	v_max_f32_e32 v21, 0, v21
	v_pk_mul_f32 v[22:23], v[22:23], v[22:23]
	v_pk_mul_f32 v[24:25], v[18:19], v[18:19]
	v_pk_mul_f32 v[28:29], v[20:21], v[20:21]
	v_cvt_pk_bf16_f32 v18, v22, v23
	v_cvt_pk_bf16_f32 v19, v24, v25
	v_cvt_pk_bf16_f32 v20, v26, v27
	v_cvt_pk_bf16_f32 v21, v28, v29
	v_add_u32_e32 v0, 0xb0, v148
	global_store_dwordx4 v[34:35], v[18:21], off offset:256
	s_nop 1
	v_and_b32_e32 v20, 0xff, v0
	v_lshlrev_b32_e32 v0, 13, v20
	v_lshl_add_u64 v[18:19], s[54:55], 0, v[0:1]
	v_mov_b32_e32 v0, v245
	s_nop 0
	v_lshl_add_u64 v[18:19], v[18:19], 0, v[142:143]
	s_mov_b64 s[50:51], -1
	s_waitcnt lgkmcnt(0)
	v_pk_mul_f32 v[10:11], v[10:11], v[0:1] op_sel_hi:[1,0]
	v_pk_mul_f32 v[16:17], v[16:17], v[0:1] op_sel_hi:[1,0]
	v_pk_mul_f32 v[14:15], v[14:15], v[0:1] op_sel_hi:[1,0]
	v_pk_mul_f32 v[12:13], v[12:13], v[0:1] op_sel_hi:[1,0]
	v_max_f32_e32 v10, 0, v10
	v_max_f32_e32 v11, 0, v11
	v_max_f32_e32 v14, 0, v14
	v_max_f32_e32 v15, 0, v15
	v_pk_mul_f32 v[20:21], v[10:11], v[10:11]
	v_max_f32_e32 v10, 0, v16
	v_max_f32_e32 v12, 0, v12
	v_max_f32_e32 v11, 0, v17
	v_max_f32_e32 v13, 0, v13
	v_pk_mul_f32 v[14:15], v[14:15], v[14:15]
	v_pk_mul_f32 v[16:17], v[10:11], v[10:11]
	v_pk_mul_f32 v[22:23], v[12:13], v[12:13]
	v_pk_mul_f32 v[2:3], v[2:3], v[0:1] op_sel_hi:[1,0]
	v_cvt_pk_bf16_f32 v10, v14, v15
	v_cvt_pk_bf16_f32 v11, v16, v17
	v_cvt_pk_bf16_f32 v12, v20, v21
	v_cvt_pk_bf16_f32 v13, v22, v23
	v_pk_mul_f32 v[8:9], v[8:9], v[0:1] op_sel_hi:[1,0]
	v_pk_mul_f32 v[6:7], v[6:7], v[0:1] op_sel_hi:[1,0]
	v_pk_mul_f32 v[4:5], v[4:5], v[0:1] op_sel_hi:[1,0]
	v_max_f32_e32 v2, 0, v2
	v_max_f32_e32 v3, 0, v3
	global_store_dwordx4 v[18:19], v[10:13], off
	v_max_f32_e32 v6, 0, v6
	v_max_f32_e32 v7, 0, v7
	v_pk_mul_f32 v[10:11], v[2:3], v[2:3]
	v_max_f32_e32 v2, 0, v8
	v_max_f32_e32 v4, 0, v4
	v_max_f32_e32 v3, 0, v9
	v_max_f32_e32 v5, 0, v5
	v_pk_mul_f32 v[6:7], v[6:7], v[6:7]
	v_pk_mul_f32 v[8:9], v[2:3], v[2:3]
	v_pk_mul_f32 v[12:13], v[4:5], v[4:5]
	v_cvt_pk_bf16_f32 v2, v6, v7
	v_cvt_pk_bf16_f32 v3, v8, v9
	v_cvt_pk_bf16_f32 v4, v10, v11
	v_cvt_pk_bf16_f32 v5, v12, v13
	global_store_dwordx4 v[18:19], v[2:5], off offset:256
	s_cbranch_vccnz .LBB0_206
	s_andn2_b64 vcc, exec, s[40:41]
	s_cbranch_vccnz .LBB0_205
	s_barrier
	s_branch .LBB0_205
